# gate-GEMM epilogue: issue both bias load pairs up front so no wait drains the 8 tile stores mid-epilogue
# speedup vs baseline: 1.0044x; 1.0044x over previous
; __device__ __forceinline__ float row_rstd(const float* ssp, int row, int fq) {
;     const f32x4 t = *((const f32x4*)(ssp + (size_t)row * 16) + fq); float s = (t[0] + t[1]) + (t[2] + t[3]); s += __shfl_xor(s, 16); s += __shfl_xor(s, 32); return rsqrtf(s * (1.0f / DM) + EPS); }
;     __device__ __forceinline__ void operator()(const f32x4 (&acc)[2][2][4][2], const Unit& u, int wr, int wc, int fr, int fq) const {
;     ...
;         const int row0 = u.pm * BM + wr * 64 + fr, col0 = u.pn * BM + 32 * wc + 8 * fq;
;         if (part == 1) {
;             float rx[2][4];
; #pragma unroll
;             for (int ai = 0; ai < 2; ++ai)
; #pragma unroll
;                 for (int m = 0; m < 4; ++m) rx[ai][m] = row_rstd(ssp, row0 + ai * HALF + m * 16, fq);
.LBB0_558:
	s_and_b64 vcc, exec, s[18:19]
	s_cbranch_vccz .LBB0_560
	v_and_b32_e32 v129, 64, v229
	v_xor_b32_e32 v128, 16, v229
	v_add_u32_e32 v129, 64, v129
	v_cmp_lt_i32_e32 vcc, v128, v129
	v_ashrrev_i32_e32 v211, 31, v210
	s_mov_b32 s10, 0x358637bd
	v_cndmask_b32_e32 v128, v229, v128, vcc
	v_lshlrev_b32_e32 v140, 2, v128
	v_xor_b32_e32 v128, 32, v229
	v_cmp_lt_i32_e32 vcc, v128, v129
	v_mov_b32_e32 v209, v193
	s_nop 0
	v_cndmask_b32_e32 v128, v229, v128, vcc
	v_lshlrev_b32_e32 v141, 2, v128
	v_lshlrev_b64 v[128:129], 6, v[210:211]
	v_lshl_add_u64 v[130:131], v[202:203], 0, v[128:129]
	global_load_dwordx4 v[156:159], v[130:131], off
	global_load_dwordx4 v[160:163], v[130:131], off offset:1024
	global_load_dwordx4 v[164:167], v[130:131], off offset:2048
	global_load_dwordx4 v[168:171], v[130:131], off offset:3072
	v_add_co_u32_e32 v188, vcc, 0x2000, v130
	s_nop 1
	v_addc_co_u32_e32 v189, vcc, 0, v131, vcc
	global_load_dwordx4 v[172:175], v[188:189], off
	global_load_dwordx4 v[176:179], v[188:189], off offset:1024
	global_load_dwordx4 v[180:183], v[188:189], off offset:2048
	global_load_dwordx4 v[184:187], v[188:189], off offset:3072
	s_waitcnt vmcnt(7)
	v_mov_b32_e32 v128, v157
	v_mov_b32_e32 v129, v158
	v_mov_b32_e32 v157, v159
	v_pk_add_f32 v[128:129], v[128:129], v[156:157]
	s_waitcnt vmcnt(6)
	v_mov_b32_e32 v136, v161
	v_mov_b32_e32 v137, v162
	v_mov_b32_e32 v161, v163
	v_pk_add_f32 v[132:133], v[136:137], v[160:161]
	v_mov_b32_e32 v135, v128
	v_mov_b32_e32 v134, v132
	v_mov_b32_e32 v128, v133
	v_pk_add_f32 v[128:129], v[134:135], v[128:129]
	ds_bpermute_b32 v133, v140, v129
	ds_bpermute_b32 v132, v140, v128
	s_waitcnt lgkmcnt(0)
	v_pk_add_f32 v[128:129], v[128:129], v[132:133]
	ds_bpermute_b32 v133, v141, v129
	ds_bpermute_b32 v132, v141, v128
	s_waitcnt lgkmcnt(0)
	v_pk_add_f32 v[132:133], v[128:129], v[132:133]
	v_mov_b64_e32 v[128:129], s[10:11]
	v_pk_fma_f32 v[132:133], v[132:133], s[38:39], v[128:129] op_sel_hi:[1,0,0]
	s_and_b32 s10, 0xffff, s52
	v_mul_f32_e32 v134, 0x4b800000, v133
	v_cmp_gt_f32_e64 s[42:43], s99, v133
	v_cmp_gt_f32_e32 vcc, s99, v132
	s_lshl_b32 s10, s10, 12
	v_cndmask_b32_e64 v133, v133, v134, s[42:43]
	v_rsq_f32_e32 v133, v133
	s_add_u32 s10, s63, s10
	s_addc_u32 s11, s64, 0
	v_mul_f32_e32 v134, 0x45800000, v133
	v_cndmask_b32_e64 v147, v133, v134, s[42:43]
	v_mul_f32_e32 v133, 0x4b800000, v132
	v_cndmask_b32_e32 v132, v132, v133, vcc
	v_rsq_f32_e32 v132, v132
	s_nop 0
	v_mul_f32_e32 v133, 0x45800000, v132
	v_cndmask_b32_e32 v145, v132, v133, vcc
	s_waitcnt vmcnt(5)
	v_mov_b32_e32 v136, v165
	v_mov_b32_e32 v137, v166
	v_mov_b32_e32 v165, v167
	v_pk_add_f32 v[136:137], v[136:137], v[164:165]
	s_waitcnt vmcnt(4)
	v_mov_b32_e32 v138, v169
	v_mov_b32_e32 v139, v170
	v_mov_b32_e32 v169, v171
	v_pk_add_f32 v[132:133], v[138:139], v[168:169]
	v_mov_b32_e32 v135, v136
	v_mov_b32_e32 v134, v132
	v_mov_b32_e32 v136, v133
	v_pk_add_f32 v[132:133], v[134:135], v[136:137]
	ds_bpermute_b32 v135, v140, v133
	ds_bpermute_b32 v134, v140, v132
	s_waitcnt lgkmcnt(0)
	v_pk_add_f32 v[132:133], v[132:133], v[134:135]
	ds_bpermute_b32 v135, v141, v133
	ds_bpermute_b32 v134, v141, v132
	s_waitcnt lgkmcnt(0)
	v_pk_add_f32 v[132:133], v[132:133], v[134:135]
	s_nop 0
	v_pk_fma_f32 v[132:133], v[132:133], s[38:39], v[128:129] op_sel_hi:[1,0,0]
	s_nop 0
	v_mul_f32_e32 v134, 0x4b800000, v133
	v_cmp_gt_f32_e64 s[42:43], s99, v133
	v_cmp_gt_f32_e32 vcc, s99, v132
	s_nop 0
	v_cndmask_b32_e64 v133, v133, v134, s[42:43]
	v_rsq_f32_e32 v133, v133
	s_nop 0
	v_mul_f32_e32 v134, 0x45800000, v133
	v_cndmask_b32_e64 v146, v133, v134, s[42:43]
	v_mul_f32_e32 v133, 0x4b800000, v132
	v_cndmask_b32_e32 v132, v132, v133, vcc
	v_rsq_f32_e32 v132, v132
	s_nop 0
	v_mul_f32_e32 v133, 0x45800000, v132
	v_cndmask_b32_e32 v143, v132, v133, vcc
	s_waitcnt vmcnt(3)
	v_mov_b32_e32 v136, v173
	v_mov_b32_e32 v137, v174
	v_mov_b32_e32 v173, v175
	v_pk_add_f32 v[136:137], v[136:137], v[172:173]
	s_waitcnt vmcnt(2)
	v_mov_b32_e32 v138, v177
	v_mov_b32_e32 v139, v178
	v_mov_b32_e32 v177, v179
	v_pk_add_f32 v[130:131], v[138:139], v[176:177]
	v_mov_b32_e32 v133, v136
	v_mov_b32_e32 v132, v130
	v_mov_b32_e32 v136, v131
	v_pk_add_f32 v[130:131], v[132:133], v[136:137]
	ds_bpermute_b32 v133, v140, v131
	ds_bpermute_b32 v132, v140, v130
	v_lshl_add_u64 v[138:139], v[208:209], 2, s[10:11]
	s_mov_b32 s10, 0x8000
	s_waitcnt lgkmcnt(0)
	v_pk_add_f32 v[130:131], v[130:131], v[132:133]
	ds_bpermute_b32 v133, v141, v131
	ds_bpermute_b32 v132, v141, v130
	s_waitcnt lgkmcnt(0)
	v_pk_add_f32 v[130:131], v[130:131], v[132:133]
	s_nop 0
	v_pk_fma_f32 v[130:131], v[130:131], s[38:39], v[128:129] op_sel_hi:[1,0,0]
	s_nop 0
	v_mul_f32_e32 v132, 0x4b800000, v131
	v_cmp_gt_f32_e64 s[42:43], s99, v131
	v_cmp_gt_f32_e32 vcc, s99, v130
	s_nop 0
	v_cndmask_b32_e64 v131, v131, v132, s[42:43]
	v_rsq_f32_e32 v131, v131
	s_nop 0
	v_mul_f32_e32 v132, 0x45800000, v131
	v_cndmask_b32_e64 v144, v131, v132, s[42:43]
	v_mul_f32_e32 v131, 0x4b800000, v130
	v_cndmask_b32_e32 v130, v130, v131, vcc
	v_rsq_f32_e32 v130, v130
	s_nop 0
	v_mul_f32_e32 v131, 0x45800000, v130
	v_cndmask_b32_e32 v142, v130, v131, vcc
	s_waitcnt vmcnt(1)
	v_mov_b32_e32 v136, v181
	v_mov_b32_e32 v137, v182
	v_mov_b32_e32 v181, v183
	v_pk_add_f32 v[136:137], v[136:137], v[180:181]
	s_waitcnt vmcnt(0)
	v_mov_b32_e32 v134, v185
	v_mov_b32_e32 v135, v186
	v_mov_b32_e32 v185, v187
	v_pk_add_f32 v[130:131], v[134:135], v[184:185]
	v_mov_b32_e32 v133, v136
	v_mov_b32_e32 v132, v130
	v_mov_b32_e32 v136, v131
	v_pk_add_f32 v[130:131], v[132:133], v[136:137]
	ds_bpermute_b32 v133, v140, v131
	ds_bpermute_b32 v132, v140, v130
	v_lshl_add_u64 v[136:137], s[30:31], 0, v[192:193]
	s_waitcnt lgkmcnt(0)
; __device__ __forceinline__ u32x4 pack8(const f32x4& a, const f32x4& b) { u32x4 w; w.x = pk2(a[0], a[1]); w.y = pk2(a[2], a[3]); w.z = pk2(b[0], b[1]); w.w = pk2(b[2], b[3]); return w; }
; __device__ __forceinline__ float sigm(float x) { return __builtin_amdgcn_rcpf(1.0f + __builtin_amdgcn_exp2f(x * -1.4426950408889634f)); }
;     __device__ __forceinline__ void operator()(const f32x4 (&acc)[2][2][4][2], const Unit& u, int wr, int wc, int fr, int fq) const {
;     ...
;                 for (int m = 0; m < 4; ++m) rx[ai][m] = row_rstd(ssp, row0 + ai * HALF + m * 16, fq);
; #pragma unroll
;             for (int bj = 0; bj < 2; ++bj) {
;                 const f32x4 bv0 = *(const f32x4*)(gb + br * 1024 + col0 + 128 * bj), bv1 = *(const f32x4*)(gb + br * 1024 + col0 + 128 * bj + 4);
; #pragma unroll
;                 for (int ai = 0; ai < 2; ++ai)
; #pragma unroll
;                     for (int m = 0; m < 4; ++m) {
;                         const f32x4 a0 = acc[ai][bj][m][0] * rx[ai][m] + bv0, a1 = acc[ai][bj][m][1] * rx[ai][m] + bv1; f32x4 o0, o1;
; #pragma unroll
;                         for (int e = 0; e < 4; ++e) { o0[e] = sigm(a0[e]); o1[e] = sigm(a1[e]); }
;                         *(u32x4*)(tmpb + ((ai * 4 + m) * 2 + bj) * 8192 + voff) = pack8(o0, o1); }
;                 asm volatile("" ::: "memory"); }
	v_pk_add_f32 v[130:131], v[130:131], v[132:133]
	ds_bpermute_b32 v133, v141, v131
	ds_bpermute_b32 v132, v141, v130
	s_waitcnt lgkmcnt(0)
	v_pk_add_f32 v[130:131], v[130:131], v[132:133]
	s_nop 0
	v_pk_fma_f32 v[128:129], v[130:131], s[38:39], v[128:129] op_sel_hi:[1,0,0]
	s_nop 0
	v_mul_f32_e32 v130, 0x4b800000, v129
	v_cmp_gt_f32_e64 s[42:43], s99, v129
	v_cmp_gt_f32_e32 vcc, s99, v128
	s_nop 0
	v_cndmask_b32_e64 v129, v129, v130, s[42:43]
	v_rsq_f32_e32 v129, v129
	s_nop 0
	v_mul_f32_e32 v130, 0x45800000, v129
	v_cndmask_b32_e64 v141, v129, v130, s[42:43]
	v_mul_f32_e32 v129, 0x4b800000, v128
	v_cndmask_b32_e32 v128, v128, v129, vcc
	v_rsq_f32_e32 v128, v128
	s_nop 0
	v_mul_f32_e32 v129, 0x45800000, v128
	v_cndmask_b32_e32 v140, v128, v129, vcc
	global_load_dwordx4 v[128:131], v[138:139], off offset:16
	global_load_dwordx4 v[132:135], v[138:139], off
	global_load_dwordx4 v[156:159], v[138:139], off offset:528
	global_load_dwordx4 v[160:163], v[138:139], off offset:512
	s_waitcnt vmcnt(3)
	v_fma_f32 v149, v120, v147, v128
	v_mul_f32_e32 v149, 0xbfb8aa3b, v149
	v_exp_f32_e32 v149, v149
	s_waitcnt vmcnt(2)
	v_fma_f32 v148, v124, v147, v132
	v_fma_f32 v151, v121, v147, v129
	v_fma_f32 v152, v126, v147, v134
	v_add_f32_e32 v149, 1.0, v149
	v_rcp_f32_e32 v150, v149
	v_fma_f32 v149, v125, v147, v133
	v_fma_f32 v153, v122, v147, v130
	v_fma_f32 v154, v127, v147, v135
	v_fma_f32 v155, v123, v147, v131
	v_mul_f32_e32 v148, 0xbfb8aa3b, v148
	v_mul_f32_e32 v149, 0xbfb8aa3b, v149
	v_mul_f32_e32 v151, 0xbfb8aa3b, v151
	v_mul_f32_e32 v152, 0xbfb8aa3b, v152
	v_mul_f32_e32 v153, 0xbfb8aa3b, v153
	v_mul_f32_e32 v154, 0xbfb8aa3b, v154
	v_mul_f32_e32 v155, 0xbfb8aa3b, v155
	v_exp_f32_e32 v148, v148
	v_exp_f32_e32 v149, v149
	v_exp_f32_e32 v151, v151
	v_exp_f32_e32 v152, v152
	v_exp_f32_e32 v153, v153
	v_exp_f32_e32 v154, v154
	v_exp_f32_e32 v155, v155
	v_add_f32_e32 v148, 1.0, v148
	v_add_f32_e32 v149, 1.0, v149
	v_add_f32_e32 v151, 1.0, v151
	v_add_f32_e32 v152, 1.0, v152
	v_add_f32_e32 v153, 1.0, v153
	v_add_f32_e32 v154, 1.0, v154
	v_add_f32_e32 v155, 1.0, v155
	v_rcp_f32_e32 v148, v148
	v_rcp_f32_e32 v149, v149
	v_rcp_f32_e32 v151, v151
	v_rcp_f32_e32 v152, v152
	v_rcp_f32_e32 v153, v153
	v_rcp_f32_e32 v154, v154
	v_rcp_f32_e32 v155, v155
	v_cvt_pk_bf16_f32 v148, v148, v149
	v_cvt_pk_bf16_f32 v150, v150, v151
	v_cvt_pk_bf16_f32 v149, v152, v154
	v_cvt_pk_bf16_f32 v151, v153, v155
	global_store_dwordx4 v192, v[148:151], s[30:31]
	v_fma_f32 v152, v118, v145, v134
	v_fma_f32 v154, v119, v145, v135
	v_fma_f32 v149, v112, v145, v128
	v_mul_f32_e32 v149, 0xbfb8aa3b, v149
	v_exp_f32_e32 v149, v149
	v_fma_f32 v148, v116, v145, v132
	v_mul_f32_e32 v148, 0xbfb8aa3b, v148
	v_fma_f32 v151, v113, v145, v129
	v_add_f32_e32 v149, 1.0, v149
	v_rcp_f32_e32 v150, v149
	v_fma_f32 v149, v117, v145, v133
	v_mul_f32_e32 v149, 0xbfb8aa3b, v149
	v_mul_f32_e32 v152, 0xbfb8aa3b, v152
	v_fma_f32 v153, v114, v145, v130
	v_mul_f32_e32 v154, 0xbfb8aa3b, v154
	v_fma_f32 v155, v115, v145, v131
	v_exp_f32_e32 v148, v148
	v_exp_f32_e32 v149, v149
	v_mul_f32_e32 v151, 0xbfb8aa3b, v151
	v_exp_f32_e32 v152, v152
	v_mul_f32_e32 v153, 0xbfb8aa3b, v153
	v_exp_f32_e32 v154, v154
	v_mul_f32_e32 v155, 0xbfb8aa3b, v155
	v_exp_f32_e32 v151, v151
	v_exp_f32_e32 v153, v153
	v_exp_f32_e32 v155, v155
	v_add_f32_e32 v148, 1.0, v148
	v_add_f32_e32 v149, 1.0, v149
	v_add_f32_e32 v152, 1.0, v152
	v_add_f32_e32 v154, 1.0, v154
	v_rcp_f32_e32 v148, v148
	v_rcp_f32_e32 v149, v149
	v_add_f32_e32 v151, 1.0, v151
	v_rcp_f32_e32 v152, v152
	v_add_f32_e32 v153, 1.0, v153
	v_rcp_f32_e32 v154, v154
	v_add_f32_e32 v155, 1.0, v155
	v_rcp_f32_e32 v151, v151
	v_rcp_f32_e32 v153, v153
	v_rcp_f32_e32 v155, v155
	v_cvt_pk_bf16_f32 v148, v148, v149
	v_cvt_pk_bf16_f32 v149, v152, v154
	v_add_co_u32_e32 v152, vcc, s83, v136
	v_cvt_pk_bf16_f32 v150, v150, v151
	v_cvt_pk_bf16_f32 v151, v153, v155
	v_addc_co_u32_e32 v153, vcc, 0, v137, vcc
	global_store_dwordx4 v[152:153], v[148:151], off
	v_fma_f32 v152, v110, v146, v134
	v_fma_f32 v154, v111, v146, v135
	v_fma_f32 v149, v104, v146, v128
	v_mul_f32_e32 v149, 0xbfb8aa3b, v149
	v_exp_f32_e32 v149, v149
	v_fma_f32 v148, v108, v146, v132
	v_mul_f32_e32 v148, 0xbfb8aa3b, v148
	v_fma_f32 v151, v105, v146, v129
	v_add_f32_e32 v149, 1.0, v149
	v_rcp_f32_e32 v150, v149
	v_fma_f32 v149, v109, v146, v133
	v_mul_f32_e32 v149, 0xbfb8aa3b, v149
	v_mul_f32_e32 v152, 0xbfb8aa3b, v152
	v_fma_f32 v153, v106, v146, v130
	v_mul_f32_e32 v154, 0xbfb8aa3b, v154
	v_fma_f32 v155, v107, v146, v131
	v_exp_f32_e32 v148, v148
	v_exp_f32_e32 v149, v149
	v_mul_f32_e32 v151, 0xbfb8aa3b, v151
	v_exp_f32_e32 v152, v152
	v_mul_f32_e32 v153, 0xbfb8aa3b, v153
	v_exp_f32_e32 v154, v154
	v_mul_f32_e32 v155, 0xbfb8aa3b, v155
	v_exp_f32_e32 v151, v151
	v_exp_f32_e32 v153, v153
	v_exp_f32_e32 v155, v155
	v_add_f32_e32 v148, 1.0, v148
	v_add_f32_e32 v149, 1.0, v149
	v_add_f32_e32 v152, 1.0, v152
	v_add_f32_e32 v154, 1.0, v154
	v_rcp_f32_e32 v148, v148
	v_rcp_f32_e32 v149, v149
	v_add_f32_e32 v151, 1.0, v151
	v_rcp_f32_e32 v152, v152
	v_add_f32_e32 v153, 1.0, v153
	v_rcp_f32_e32 v154, v154
	v_add_f32_e32 v155, 1.0, v155
	v_rcp_f32_e32 v151, v151
	v_rcp_f32_e32 v153, v153
	v_rcp_f32_e32 v155, v155
	v_cvt_pk_bf16_f32 v148, v148, v149
	v_cvt_pk_bf16_f32 v149, v152, v154
	v_add_co_u32_e32 v152, vcc, s10, v136
	v_cvt_pk_bf16_f32 v150, v150, v151
	v_cvt_pk_bf16_f32 v151, v153, v155
	v_addc_co_u32_e32 v153, vcc, 0, v137, vcc
	global_store_dwordx4 v[152:153], v[148:151], off
	v_fma_f32 v152, v102, v143, v134
	v_fma_f32 v154, v103, v143, v135
	v_fma_f32 v149, v96, v143, v128
	v_mul_f32_e32 v149, 0xbfb8aa3b, v149
; __device__ __forceinline__ u32x4 pack8(const f32x4& a, const f32x4& b) { u32x4 w; w.x = pk2(a[0], a[1]); w.y = pk2(a[2], a[3]); w.z = pk2(b[0], b[1]); w.w = pk2(b[2], b[3]); return w; }
; __device__ __forceinline__ float sigm(float x) { return __builtin_amdgcn_rcpf(1.0f + __builtin_amdgcn_exp2f(x * -1.4426950408889634f)); }
;     __device__ __forceinline__ void operator()(const f32x4 (&acc)[2][2][4][2], const Unit& u, int wr, int wc, int fr, int fq) const {
;     ...
;             for (int bj = 0; bj < 2; ++bj) {
;                 const f32x4 bv0 = *(const f32x4*)(gb + br * 1024 + col0 + 128 * bj), bv1 = *(const f32x4*)(gb + br * 1024 + col0 + 128 * bj + 4);
; #pragma unroll
;                 for (int ai = 0; ai < 2; ++ai)
; #pragma unroll
;                     for (int m = 0; m < 4; ++m) {
;                         const f32x4 a0 = acc[ai][bj][m][0] * rx[ai][m] + bv0, a1 = acc[ai][bj][m][1] * rx[ai][m] + bv1; f32x4 o0, o1;
; #pragma unroll
;                         for (int e = 0; e < 4; ++e) { o0[e] = sigm(a0[e]); o1[e] = sigm(a1[e]); }
;                         *(u32x4*)(tmpb + ((ai * 4 + m) * 2 + bj) * 8192 + voff) = pack8(o0, o1); }
;                 asm volatile("" ::: "memory"); }
	v_exp_f32_e32 v149, v149
	v_fma_f32 v148, v100, v143, v132
	v_mul_f32_e32 v148, 0xbfb8aa3b, v148
	v_fma_f32 v151, v97, v143, v129
	v_add_f32_e32 v149, 1.0, v149
	v_rcp_f32_e32 v150, v149
	v_fma_f32 v149, v101, v143, v133
	v_mul_f32_e32 v149, 0xbfb8aa3b, v149
	v_mul_f32_e32 v152, 0xbfb8aa3b, v152
	v_fma_f32 v153, v98, v143, v130
	v_mul_f32_e32 v154, 0xbfb8aa3b, v154
	v_fma_f32 v155, v99, v143, v131
	v_exp_f32_e32 v148, v148
	v_exp_f32_e32 v149, v149
	v_mul_f32_e32 v151, 0xbfb8aa3b, v151
	v_exp_f32_e32 v152, v152
	v_mul_f32_e32 v153, 0xbfb8aa3b, v153
	v_exp_f32_e32 v154, v154
	v_mul_f32_e32 v155, 0xbfb8aa3b, v155
	v_exp_f32_e32 v151, v151
	v_exp_f32_e32 v153, v153
	v_exp_f32_e32 v155, v155
	v_add_f32_e32 v148, 1.0, v148
	v_add_f32_e32 v149, 1.0, v149
	v_add_f32_e32 v152, 1.0, v152
	v_add_f32_e32 v154, 1.0, v154
	v_rcp_f32_e32 v148, v148
	v_rcp_f32_e32 v149, v149
	v_add_f32_e32 v151, 1.0, v151
	v_rcp_f32_e32 v152, v152
	v_add_f32_e32 v153, 1.0, v153
	v_rcp_f32_e32 v154, v154
	v_add_f32_e32 v155, 1.0, v155
	v_rcp_f32_e32 v151, v151
	v_rcp_f32_e32 v153, v153
	v_rcp_f32_e32 v155, v155
	s_mov_b32 s10, 0xc000
	v_cvt_pk_bf16_f32 v148, v148, v149
	v_cvt_pk_bf16_f32 v149, v152, v154
	v_add_co_u32_e32 v152, vcc, s10, v136
	v_cvt_pk_bf16_f32 v150, v150, v151
	v_cvt_pk_bf16_f32 v151, v153, v155
	v_addc_co_u32_e32 v153, vcc, 0, v137, vcc
	global_store_dwordx4 v[152:153], v[148:151], off
	v_fma_f32 v152, v62, v144, v134
	v_fma_f32 v154, v63, v144, v135
	v_fma_f32 v149, v56, v144, v128
	v_mul_f32_e32 v149, 0xbfb8aa3b, v149
	v_exp_f32_e32 v149, v149
	v_fma_f32 v148, v60, v144, v132
	v_mul_f32_e32 v148, 0xbfb8aa3b, v148
	v_fma_f32 v151, v57, v144, v129
	v_add_f32_e32 v149, 1.0, v149
	v_rcp_f32_e32 v150, v149
	v_fma_f32 v149, v61, v144, v133
	v_mul_f32_e32 v149, 0xbfb8aa3b, v149
	v_mul_f32_e32 v152, 0xbfb8aa3b, v152
	v_fma_f32 v153, v58, v144, v130
	v_mul_f32_e32 v154, 0xbfb8aa3b, v154
	v_fma_f32 v155, v59, v144, v131
	v_exp_f32_e32 v148, v148
	v_exp_f32_e32 v149, v149
	v_mul_f32_e32 v151, 0xbfb8aa3b, v151
	v_exp_f32_e32 v152, v152
	v_mul_f32_e32 v153, 0xbfb8aa3b, v153
	v_exp_f32_e32 v154, v154
	v_mul_f32_e32 v155, 0xbfb8aa3b, v155
	v_exp_f32_e32 v151, v151
	v_exp_f32_e32 v153, v153
	v_exp_f32_e32 v155, v155
	v_add_f32_e32 v148, 1.0, v148
	v_add_f32_e32 v149, 1.0, v149
	v_add_f32_e32 v152, 1.0, v152
	v_add_f32_e32 v154, 1.0, v154
	v_rcp_f32_e32 v148, v148
	v_rcp_f32_e32 v149, v149
	v_add_f32_e32 v151, 1.0, v151
	v_rcp_f32_e32 v152, v152
	v_add_f32_e32 v153, 1.0, v153
	v_rcp_f32_e32 v154, v154
	v_add_f32_e32 v155, 1.0, v155
	v_rcp_f32_e32 v151, v151
	v_rcp_f32_e32 v153, v153
	v_rcp_f32_e32 v155, v155
	v_cvt_pk_bf16_f32 v148, v148, v149
	v_cvt_pk_bf16_f32 v149, v152, v154
	v_add_co_u32_e32 v152, vcc, s4, v136
	v_cvt_pk_bf16_f32 v150, v150, v151
	v_cvt_pk_bf16_f32 v151, v153, v155
	v_addc_co_u32_e32 v153, vcc, 0, v137, vcc
	global_store_dwordx4 v[152:153], v[148:151], off
	v_fma_f32 v152, v54, v142, v134
	v_fma_f32 v154, v55, v142, v135
	v_fma_f32 v149, v48, v142, v128
	v_mul_f32_e32 v149, 0xbfb8aa3b, v149
	v_exp_f32_e32 v149, v149
	v_fma_f32 v148, v52, v142, v132
	v_mul_f32_e32 v148, 0xbfb8aa3b, v148
	v_fma_f32 v151, v49, v142, v129
	v_add_f32_e32 v149, 1.0, v149
	v_rcp_f32_e32 v150, v149
	v_fma_f32 v149, v53, v142, v133
	v_mul_f32_e32 v149, 0xbfb8aa3b, v149
	v_mul_f32_e32 v152, 0xbfb8aa3b, v152
	v_fma_f32 v153, v50, v142, v130
	v_mul_f32_e32 v154, 0xbfb8aa3b, v154
	v_fma_f32 v155, v51, v142, v131
	v_exp_f32_e32 v148, v148
	v_exp_f32_e32 v149, v149
	v_mul_f32_e32 v151, 0xbfb8aa3b, v151
	v_exp_f32_e32 v152, v152
	v_mul_f32_e32 v153, 0xbfb8aa3b, v153
	v_exp_f32_e32 v154, v154
	v_mul_f32_e32 v155, 0xbfb8aa3b, v155
	v_exp_f32_e32 v151, v151
	v_exp_f32_e32 v153, v153
	v_exp_f32_e32 v155, v155
	v_add_f32_e32 v148, 1.0, v148
	v_add_f32_e32 v149, 1.0, v149
	v_add_f32_e32 v152, 1.0, v152
	v_add_f32_e32 v154, 1.0, v154
	v_rcp_f32_e32 v148, v148
	v_rcp_f32_e32 v149, v149
	v_add_f32_e32 v151, 1.0, v151
	v_rcp_f32_e32 v152, v152
	v_add_f32_e32 v153, 1.0, v153
	v_rcp_f32_e32 v154, v154
	v_add_f32_e32 v155, 1.0, v155
	v_rcp_f32_e32 v151, v151
	v_rcp_f32_e32 v153, v153
	v_rcp_f32_e32 v155, v155
	v_cvt_pk_bf16_f32 v148, v148, v149
	v_cvt_pk_bf16_f32 v149, v152, v154
	v_add_co_u32_e32 v152, vcc, s6, v136
	v_cvt_pk_bf16_f32 v150, v150, v151
	v_cvt_pk_bf16_f32 v151, v153, v155
	v_addc_co_u32_e32 v153, vcc, 0, v137, vcc
	global_store_dwordx4 v[152:153], v[148:151], off
	v_fma_f32 v152, v46, v141, v134
	v_fma_f32 v154, v47, v141, v135
	v_fma_f32 v149, v40, v141, v128
	v_mul_f32_e32 v149, 0xbfb8aa3b, v149
	v_exp_f32_e32 v149, v149
	v_fma_f32 v148, v44, v141, v132
	v_mul_f32_e32 v148, 0xbfb8aa3b, v148
	v_fma_f32 v151, v41, v141, v129
	v_add_f32_e32 v149, 1.0, v149
	v_rcp_f32_e32 v150, v149
	v_fma_f32 v149, v45, v141, v133
	v_mul_f32_e32 v149, 0xbfb8aa3b, v149
	v_mul_f32_e32 v152, 0xbfb8aa3b, v152
	v_fma_f32 v153, v42, v141, v130
	v_mul_f32_e32 v154, 0xbfb8aa3b, v154
	v_fma_f32 v155, v43, v141, v131
	v_exp_f32_e32 v148, v148
	v_exp_f32_e32 v149, v149
	v_mul_f32_e32 v151, 0xbfb8aa3b, v151
	v_exp_f32_e32 v152, v152
	v_mul_f32_e32 v153, 0xbfb8aa3b, v153
	v_exp_f32_e32 v154, v154
	v_mul_f32_e32 v155, 0xbfb8aa3b, v155
	v_exp_f32_e32 v151, v151
	v_exp_f32_e32 v153, v153
	v_exp_f32_e32 v155, v155
	v_add_f32_e32 v148, 1.0, v148
	v_add_f32_e32 v149, 1.0, v149
	v_add_f32_e32 v152, 1.0, v152
	v_add_f32_e32 v154, 1.0, v154
	v_fma_f32 v128, v32, v140, v128
	v_rcp_f32_e32 v148, v148
	v_rcp_f32_e32 v149, v149
	v_add_f32_e32 v151, 1.0, v151
	v_rcp_f32_e32 v152, v152
	v_add_f32_e32 v153, 1.0, v153
	v_rcp_f32_e32 v154, v154
	v_add_f32_e32 v155, 1.0, v155
	v_mul_f32_e32 v128, 0xbfb8aa3b, v128
; __device__ __forceinline__ u32x4 pack8(const f32x4& a, const f32x4& b) { u32x4 w; w.x = pk2(a[0], a[1]); w.y = pk2(a[2], a[3]); w.z = pk2(b[0], b[1]); w.w = pk2(b[2], b[3]); return w; }
; __device__ __forceinline__ float sigm(float x) { return __builtin_amdgcn_rcpf(1.0f + __builtin_amdgcn_exp2f(x * -1.4426950408889634f)); }
;     __device__ __forceinline__ void operator()(const f32x4 (&acc)[2][2][4][2], const Unit& u, int wr, int wc, int fr, int fq) const {
;     ...
;             for (int bj = 0; bj < 2; ++bj) {
;                 const f32x4 bv0 = *(const f32x4*)(gb + br * 1024 + col0 + 128 * bj), bv1 = *(const f32x4*)(gb + br * 1024 + col0 + 128 * bj + 4);
; #pragma unroll
;                 for (int ai = 0; ai < 2; ++ai)
; #pragma unroll
;                     for (int m = 0; m < 4; ++m) {
;                         const f32x4 a0 = acc[ai][bj][m][0] * rx[ai][m] + bv0, a1 = acc[ai][bj][m][1] * rx[ai][m] + bv1; f32x4 o0, o1;
; #pragma unroll
;                         for (int e = 0; e < 4; ++e) { o0[e] = sigm(a0[e]); o1[e] = sigm(a1[e]); }
;                         *(u32x4*)(tmpb + ((ai * 4 + m) * 2 + bj) * 8192 + voff) = pack8(o0, o1); }
;                 asm volatile("" ::: "memory"); }
	v_fma_f32 v129, v33, v140, v129
	v_rcp_f32_e32 v151, v151
	v_rcp_f32_e32 v153, v153
	v_rcp_f32_e32 v155, v155
	v_exp_f32_e32 v128, v128
	v_mul_f32_e32 v129, 0xbfb8aa3b, v129
	v_fma_f32 v130, v34, v140, v130
	v_exp_f32_e32 v129, v129
	v_mul_f32_e32 v130, 0xbfb8aa3b, v130
	v_exp_f32_e32 v130, v130
	v_cvt_pk_bf16_f32 v148, v148, v149
	v_cvt_pk_bf16_f32 v149, v152, v154
	v_add_co_u32_e32 v152, vcc, s79, v136
	v_cvt_pk_bf16_f32 v150, v150, v151
	v_cvt_pk_bf16_f32 v151, v153, v155
	v_addc_co_u32_e32 v153, vcc, 0, v137, vcc
	v_add_f32_e32 v128, 1.0, v128
	global_store_dwordx4 v[152:153], v[148:151], off
	v_fma_f32 v132, v36, v140, v132
	v_add_f32_e32 v129, 1.0, v129
	v_rcp_f32_e32 v148, v128
	v_fma_f32 v128, v37, v140, v133
	v_mul_f32_e32 v132, 0xbfb8aa3b, v132
	v_mul_f32_e32 v128, 0xbfb8aa3b, v128
	v_rcp_f32_e32 v133, v129
	v_fma_f32 v129, v38, v140, v134
	v_add_f32_e32 v130, 1.0, v130
	v_fmac_f32_e32 v135, v39, v140
	v_fmac_f32_e32 v131, v35, v140
	v_exp_f32_e32 v132, v132
	v_exp_f32_e32 v128, v128
	v_mul_f32_e32 v129, 0xbfb8aa3b, v129
	v_rcp_f32_e32 v134, v130
	v_mul_f32_e32 v130, 0xbfb8aa3b, v135
	v_mul_f32_e32 v131, 0xbfb8aa3b, v131
	v_exp_f32_e32 v129, v129
	v_exp_f32_e32 v130, v130
	v_exp_f32_e32 v131, v131
	v_add_f32_e32 v132, 1.0, v132
	v_add_f32_e32 v128, 1.0, v128
	v_rcp_f32_e32 v132, v132
	v_rcp_f32_e32 v128, v128
	v_add_f32_e32 v129, 1.0, v129
	v_add_f32_e32 v130, 1.0, v130
	v_add_f32_e32 v131, 1.0, v131
	v_rcp_f32_e32 v129, v129
	v_rcp_f32_e32 v130, v130
	v_rcp_f32_e32 v131, v131
	v_cvt_pk_bf16_f32 v128, v132, v128
	v_add_co_u32_e32 v132, vcc, s87, v136
	v_cvt_pk_bf16_f32 v129, v129, v130
	v_cvt_pk_bf16_f32 v130, v148, v133
	v_cvt_pk_bf16_f32 v131, v134, v131
	v_addc_co_u32_e32 v133, vcc, 0, v137, vcc
	global_store_dwordx4 v[132:133], v[128:131], off
	s_movk_i32 s10, 0x6000
	s_waitcnt vmcnt(8)
	v_fma_f32 v149, v89, v147, v157
	v_mul_f32_e32 v149, 0xbfb8aa3b, v149
	v_exp_f32_e32 v149, v149
	s_waitcnt vmcnt(8)
	v_fma_f32 v138, v92, v147, v160
	v_fma_f32 v148, v93, v147, v161
	v_mul_f32_e32 v138, 0xbfb8aa3b, v138
	v_add_f32_e32 v149, 1.0, v149
	v_fma_f32 v139, v88, v147, v156
	v_mul_f32_e32 v148, 0xbfb8aa3b, v148
	v_rcp_f32_e32 v150, v149
	v_fma_f32 v149, v94, v147, v162
	v_fma_f32 v151, v90, v147, v158
	v_fma_f32 v152, v95, v147, v163
	v_fma_f32 v147, v91, v147, v159
	v_exp_f32_e32 v138, v138
	v_mul_f32_e32 v139, 0xbfb8aa3b, v139
	v_exp_f32_e32 v148, v148
	v_mul_f32_e32 v149, 0xbfb8aa3b, v149
	v_mul_f32_e32 v151, 0xbfb8aa3b, v151
	v_mul_f32_e32 v152, 0xbfb8aa3b, v152
	v_mul_f32_e32 v147, 0xbfb8aa3b, v147
	v_exp_f32_e32 v139, v139
	v_exp_f32_e32 v149, v149
	v_exp_f32_e32 v151, v151
	v_exp_f32_e32 v152, v152
	v_exp_f32_e32 v147, v147
	v_add_f32_e32 v138, 1.0, v138
	v_add_f32_e32 v148, 1.0, v148
	v_rcp_f32_e32 v138, v138
	v_add_f32_e32 v139, 1.0, v139
	v_rcp_f32_e32 v148, v148
	v_add_f32_e32 v149, 1.0, v149
	v_add_f32_e32 v151, 1.0, v151
	v_add_f32_e32 v152, 1.0, v152
	v_add_f32_e32 v147, 1.0, v147
	v_rcp_f32_e32 v139, v139
	v_rcp_f32_e32 v149, v149
	v_rcp_f32_e32 v151, v151
	v_rcp_f32_e32 v152, v152
	v_rcp_f32_e32 v147, v147
	v_cvt_pk_bf16_f32 v148, v138, v148
	v_add_co_u32_e32 v138, vcc, s82, v136
	v_cvt_pk_bf16_f32 v149, v149, v152
	v_cvt_pk_bf16_f32 v150, v139, v150
	v_cvt_pk_bf16_f32 v151, v151, v147
	v_addc_co_u32_e32 v139, vcc, 0, v137, vcc
	global_store_dwordx4 v[138:139], v[148:151], off
	v_fma_f32 v138, v84, v145, v160
	v_fma_f32 v147, v85, v145, v161
	v_fma_f32 v148, v81, v145, v157
	v_mul_f32_e32 v148, 0xbfb8aa3b, v148
	v_exp_f32_e32 v148, v148
	v_mul_f32_e32 v138, 0xbfb8aa3b, v138
	v_mul_f32_e32 v147, 0xbfb8aa3b, v147
	v_exp_f32_e32 v138, v138
	v_add_f32_e32 v148, 1.0, v148
	v_rcp_f32_e32 v150, v148
	v_fma_f32 v148, v86, v145, v162
	v_mul_f32_e32 v148, 0xbfb8aa3b, v148
	v_exp_f32_e32 v148, v148
	v_exp_f32_e32 v147, v147
	v_fma_f32 v139, v80, v145, v156
	v_add_f32_e32 v138, 1.0, v138
	v_add_f32_e32 v148, 1.0, v148
	v_rcp_f32_e32 v149, v148
	v_fma_f32 v148, v82, v145, v158
	v_mul_f32_e32 v148, 0xbfb8aa3b, v148
	v_exp_f32_e32 v148, v148
	v_mul_f32_e32 v139, 0xbfb8aa3b, v139
	v_add_f32_e32 v147, 1.0, v147
	v_rcp_f32_e32 v138, v138
	v_add_f32_e32 v148, 1.0, v148
	v_rcp_f32_e32 v151, v148
	v_fma_f32 v148, v87, v145, v163
	v_mul_f32_e32 v148, 0xbfb8aa3b, v148
	v_fma_f32 v145, v83, v145, v159
	v_exp_f32_e32 v148, v148
	v_mul_f32_e32 v145, 0xbfb8aa3b, v145
	v_exp_f32_e32 v139, v139
	v_rcp_f32_e32 v147, v147
	v_exp_f32_e32 v145, v145
	v_add_f32_e32 v148, 1.0, v148
	v_add_f32_e32 v139, 1.0, v139
	v_rcp_f32_e32 v152, v148
	v_add_f32_e32 v145, 1.0, v145
	v_cvt_pk_bf16_f32 v148, v138, v147
	v_fma_f32 v147, v73, v146, v157
	v_rcp_f32_e32 v139, v139
	v_rcp_f32_e32 v145, v145
	v_mul_f32_e32 v147, 0xbfb8aa3b, v147
	v_exp_f32_e32 v147, v147
	v_add_co_u32_e32 v138, vcc, s10, v136
	v_cvt_pk_bf16_f32 v149, v149, v152
	v_cvt_pk_bf16_f32 v150, v139, v150
	v_cvt_pk_bf16_f32 v151, v151, v145
	v_addc_co_u32_e32 v139, vcc, 0, v137, vcc
	global_store_dwordx4 v[138:139], v[148:151], off
	v_fma_f32 v138, v76, v146, v160
	v_fma_f32 v145, v77, v146, v161
	v_add_f32_e32 v147, 1.0, v147
	v_mul_f32_e32 v138, 0xbfb8aa3b, v138
	v_fma_f32 v139, v72, v146, v156
	v_mul_f32_e32 v145, 0xbfb8aa3b, v145
	v_rcp_f32_e32 v148, v147
	v_fma_f32 v147, v78, v146, v162
	v_fma_f32 v149, v74, v146, v158
	v_fma_f32 v150, v79, v146, v163
	v_fma_f32 v146, v75, v146, v159
	v_exp_f32_e32 v138, v138
	v_mul_f32_e32 v139, 0xbfb8aa3b, v139
	v_exp_f32_e32 v145, v145
	v_mul_f32_e32 v147, 0xbfb8aa3b, v147
	v_mul_f32_e32 v149, 0xbfb8aa3b, v149
	v_mul_f32_e32 v150, 0xbfb8aa3b, v150
	v_mul_f32_e32 v146, 0xbfb8aa3b, v146
	v_exp_f32_e32 v139, v139
	v_exp_f32_e32 v147, v147
	v_exp_f32_e32 v149, v149
; __device__ __forceinline__ u32x4 pack8(const f32x4& a, const f32x4& b) { u32x4 w; w.x = pk2(a[0], a[1]); w.y = pk2(a[2], a[3]); w.z = pk2(b[0], b[1]); w.w = pk2(b[2], b[3]); return w; }
; __device__ __forceinline__ float sigm(float x) { return __builtin_amdgcn_rcpf(1.0f + __builtin_amdgcn_exp2f(x * -1.4426950408889634f)); }
;     __device__ __forceinline__ void operator()(const f32x4 (&acc)[2][2][4][2], const Unit& u, int wr, int wc, int fr, int fq) const {
;     ...
;             for (int bj = 0; bj < 2; ++bj) {
;                 const f32x4 bv0 = *(const f32x4*)(gb + br * 1024 + col0 + 128 * bj), bv1 = *(const f32x4*)(gb + br * 1024 + col0 + 128 * bj + 4);
; #pragma unroll
;                 for (int ai = 0; ai < 2; ++ai)
; #pragma unroll
;                     for (int m = 0; m < 4; ++m) {
;                         const f32x4 a0 = acc[ai][bj][m][0] * rx[ai][m] + bv0, a1 = acc[ai][bj][m][1] * rx[ai][m] + bv1; f32x4 o0, o1;
; #pragma unroll
;                         for (int e = 0; e < 4; ++e) { o0[e] = sigm(a0[e]); o1[e] = sigm(a1[e]); }
;                         *(u32x4*)(tmpb + ((ai * 4 + m) * 2 + bj) * 8192 + voff) = pack8(o0, o1); }
;                 asm volatile("" ::: "memory"); }
	v_exp_f32_e32 v150, v150
	v_exp_f32_e32 v146, v146
	v_add_f32_e32 v138, 1.0, v138
	v_add_f32_e32 v145, 1.0, v145
	v_rcp_f32_e32 v138, v138
	v_add_f32_e32 v139, 1.0, v139
	v_rcp_f32_e32 v145, v145
	v_add_f32_e32 v147, 1.0, v147
	v_add_f32_e32 v149, 1.0, v149
	v_add_f32_e32 v150, 1.0, v150
	v_add_f32_e32 v146, 1.0, v146
	v_rcp_f32_e32 v139, v139
	v_rcp_f32_e32 v147, v147
	v_rcp_f32_e32 v149, v149
	v_rcp_f32_e32 v150, v150
	v_rcp_f32_e32 v151, v146
	s_mov_b32 s10, 0xa000
	v_cvt_pk_bf16_f32 v146, v138, v145
	v_add_co_u32_e32 v138, vcc, s10, v136
	v_cvt_pk_bf16_f32 v147, v147, v150
	v_cvt_pk_bf16_f32 v148, v139, v148
	v_cvt_pk_bf16_f32 v149, v149, v151
	v_addc_co_u32_e32 v139, vcc, 0, v137, vcc
	global_store_dwordx4 v[138:139], v[146:149], off
	v_fma_f32 v138, v68, v143, v160
	v_fma_f32 v145, v69, v143, v161
	v_fma_f32 v146, v65, v143, v157
	v_mul_f32_e32 v146, 0xbfb8aa3b, v146
	v_exp_f32_e32 v146, v146
	v_mul_f32_e32 v138, 0xbfb8aa3b, v138
	v_mul_f32_e32 v145, 0xbfb8aa3b, v145
	v_exp_f32_e32 v138, v138
	v_add_f32_e32 v146, 1.0, v146
	v_rcp_f32_e32 v148, v146
	v_fma_f32 v146, v70, v143, v162
	v_mul_f32_e32 v146, 0xbfb8aa3b, v146
	v_exp_f32_e32 v146, v146
	v_exp_f32_e32 v145, v145
	v_fma_f32 v139, v64, v143, v156
	v_add_f32_e32 v138, 1.0, v138
	v_add_f32_e32 v146, 1.0, v146
	v_rcp_f32_e32 v147, v146
	v_fma_f32 v146, v66, v143, v158
	v_mul_f32_e32 v146, 0xbfb8aa3b, v146
	v_exp_f32_e32 v146, v146
	v_mul_f32_e32 v139, 0xbfb8aa3b, v139
	v_add_f32_e32 v145, 1.0, v145
	v_rcp_f32_e32 v138, v138
	v_add_f32_e32 v146, 1.0, v146
	v_rcp_f32_e32 v149, v146
	v_fma_f32 v146, v71, v143, v163
	v_mul_f32_e32 v146, 0xbfb8aa3b, v146
	v_fma_f32 v143, v67, v143, v159
	v_exp_f32_e32 v146, v146
	v_mul_f32_e32 v143, 0xbfb8aa3b, v143
	v_exp_f32_e32 v139, v139
	v_rcp_f32_e32 v145, v145
	v_exp_f32_e32 v143, v143
	v_add_f32_e32 v146, 1.0, v146
	v_add_f32_e32 v139, 1.0, v139
	v_rcp_f32_e32 v150, v146
	v_add_f32_e32 v143, 1.0, v143
	v_cvt_pk_bf16_f32 v146, v138, v145
	v_fma_f32 v145, v25, v144, v157
	v_rcp_f32_e32 v139, v139
	v_rcp_f32_e32 v143, v143
	v_mul_f32_e32 v145, 0xbfb8aa3b, v145
	v_exp_f32_e32 v145, v145
	v_add_co_u32_e32 v138, vcc, s98, v136
	v_cvt_pk_bf16_f32 v147, v147, v150
	v_cvt_pk_bf16_f32 v148, v139, v148
	v_cvt_pk_bf16_f32 v149, v149, v143
	v_addc_co_u32_e32 v139, vcc, 0, v137, vcc
	global_store_dwordx4 v[138:139], v[146:149], off
	v_fma_f32 v138, v28, v144, v160
	v_fma_f32 v143, v29, v144, v161
	v_add_f32_e32 v145, 1.0, v145
	v_mul_f32_e32 v138, 0xbfb8aa3b, v138
	v_fma_f32 v139, v24, v144, v156
	v_mul_f32_e32 v143, 0xbfb8aa3b, v143
	v_rcp_f32_e32 v146, v145
	v_fma_f32 v145, v30, v144, v162
	v_fma_f32 v147, v26, v144, v158
	v_fma_f32 v148, v31, v144, v163
	v_fma_f32 v144, v27, v144, v159
	v_exp_f32_e32 v138, v138
	v_mul_f32_e32 v139, 0xbfb8aa3b, v139
	v_exp_f32_e32 v143, v143
	v_mul_f32_e32 v145, 0xbfb8aa3b, v145
	v_mul_f32_e32 v147, 0xbfb8aa3b, v147
	v_mul_f32_e32 v148, 0xbfb8aa3b, v148
	v_mul_f32_e32 v144, 0xbfb8aa3b, v144
	v_exp_f32_e32 v139, v139
	v_exp_f32_e32 v145, v145
	v_exp_f32_e32 v147, v147
	v_exp_f32_e32 v148, v148
	v_exp_f32_e32 v144, v144
	v_add_f32_e32 v138, 1.0, v138
	v_add_f32_e32 v143, 1.0, v143
	v_rcp_f32_e32 v138, v138
	v_add_f32_e32 v139, 1.0, v139
	v_rcp_f32_e32 v143, v143
	v_add_f32_e32 v145, 1.0, v145
	v_add_f32_e32 v147, 1.0, v147
	v_add_f32_e32 v148, 1.0, v148
	v_add_f32_e32 v144, 1.0, v144
	v_rcp_f32_e32 v139, v139
	v_rcp_f32_e32 v145, v145
	v_rcp_f32_e32 v147, v147
	v_rcp_f32_e32 v148, v148
	v_rcp_f32_e32 v149, v144
	v_cvt_pk_bf16_f32 v144, v138, v143
	v_add_co_u32_e32 v138, vcc, s5, v136
	v_cvt_pk_bf16_f32 v145, v145, v148
	v_cvt_pk_bf16_f32 v146, v139, v146
	v_cvt_pk_bf16_f32 v147, v147, v149
	v_addc_co_u32_e32 v139, vcc, 0, v137, vcc
	global_store_dwordx4 v[138:139], v[144:147], off
	v_fma_f32 v138, v20, v142, v160
	v_fma_f32 v143, v21, v142, v161
	v_mul_f32_e32 v138, 0xbfb8aa3b, v138
	v_fma_f32 v139, v16, v142, v156
	v_mul_f32_e32 v143, 0xbfb8aa3b, v143
	v_fma_f32 v144, v17, v142, v157
	v_fma_f32 v145, v22, v142, v162
	v_fma_f32 v146, v18, v142, v158
	v_fma_f32 v147, v23, v142, v163
	v_fma_f32 v142, v19, v142, v159
	v_exp_f32_e32 v138, v138
; __device__ __forceinline__ u32x4 pack8(const f32x4& a, const f32x4& b) { u32x4 w; w.x = pk2(a[0], a[1]); w.y = pk2(a[2], a[3]); w.z = pk2(b[0], b[1]); w.w = pk2(b[2], b[3]); return w; }
; __device__ __forceinline__ float sigm(float x) { return __builtin_amdgcn_rcpf(1.0f + __builtin_amdgcn_exp2f(x * -1.4426950408889634f)); }
;     __device__ __forceinline__ void operator()(const f32x4 (&acc)[2][2][4][2], const Unit& u, int wr, int wc, int fr, int fq) const {
;     ...
;             for (int bj = 0; bj < 2; ++bj) {
;                 const f32x4 bv0 = *(const f32x4*)(gb + br * 1024 + col0 + 128 * bj), bv1 = *(const f32x4*)(gb + br * 1024 + col0 + 128 * bj + 4);
; #pragma unroll
;                 for (int ai = 0; ai < 2; ++ai)
; #pragma unroll
;                     for (int m = 0; m < 4; ++m) {
;                         const f32x4 a0 = acc[ai][bj][m][0] * rx[ai][m] + bv0, a1 = acc[ai][bj][m][1] * rx[ai][m] + bv1; f32x4 o0, o1;
; #pragma unroll
;                         for (int e = 0; e < 4; ++e) { o0[e] = sigm(a0[e]); o1[e] = sigm(a1[e]); }
;                         *(u32x4*)(tmpb + ((ai * 4 + m) * 2 + bj) * 8192 + voff) = pack8(o0, o1); }
;                 asm volatile("" ::: "memory"); }
	v_mul_f32_e32 v139, 0xbfb8aa3b, v139
	v_exp_f32_e32 v143, v143
	v_mul_f32_e32 v144, 0xbfb8aa3b, v144
	v_mul_f32_e32 v145, 0xbfb8aa3b, v145
	v_mul_f32_e32 v146, 0xbfb8aa3b, v146
	v_mul_f32_e32 v147, 0xbfb8aa3b, v147
	v_mul_f32_e32 v142, 0xbfb8aa3b, v142
	v_exp_f32_e32 v139, v139
	v_exp_f32_e32 v144, v144
	v_exp_f32_e32 v145, v145
	v_exp_f32_e32 v146, v146
	v_exp_f32_e32 v147, v147
	v_exp_f32_e32 v142, v142
	v_add_f32_e32 v138, 1.0, v138
	v_add_f32_e32 v143, 1.0, v143
	v_rcp_f32_e32 v138, v138
	v_add_f32_e32 v139, 1.0, v139
	v_rcp_f32_e32 v143, v143
	v_add_f32_e32 v144, 1.0, v144
	v_add_f32_e32 v145, 1.0, v145
	v_add_f32_e32 v146, 1.0, v146
	v_add_f32_e32 v147, 1.0, v147
	v_add_f32_e32 v142, 1.0, v142
	v_rcp_f32_e32 v139, v139
	v_rcp_f32_e32 v144, v144
	v_rcp_f32_e32 v145, v145
	v_rcp_f32_e32 v146, v146
	v_rcp_f32_e32 v147, v147
	v_rcp_f32_e32 v148, v142
	v_cvt_pk_bf16_f32 v142, v138, v143
	v_add_co_u32_e32 v138, vcc, s7, v136
	v_cvt_pk_bf16_f32 v143, v145, v147
	v_cvt_pk_bf16_f32 v144, v139, v144
	v_cvt_pk_bf16_f32 v145, v146, v148
	v_addc_co_u32_e32 v139, vcc, 0, v137, vcc
	global_store_dwordx4 v[138:139], v[142:145], off
	v_fma_f32 v138, v12, v141, v160
	v_mul_f32_e32 v138, 0xbfb8aa3b, v138
	v_fma_f32 v143, v9, v141, v157
	v_mul_f32_e32 v143, 0xbfb8aa3b, v143
	v_exp_f32_e32 v143, v143
	v_fma_f32 v142, v13, v141, v161
	v_fma_f32 v139, v8, v141, v156
	v_mul_f32_e32 v142, 0xbfb8aa3b, v142
	v_add_f32_e32 v143, 1.0, v143
	v_rcp_f32_e32 v144, v143
	v_fma_f32 v143, v14, v141, v162
	v_fma_f32 v145, v10, v141, v158
	v_fma_f32 v146, v15, v141, v163
	v_fma_f32 v141, v11, v141, v159
	v_exp_f32_e32 v138, v138
	v_mul_f32_e32 v139, 0xbfb8aa3b, v139
	v_exp_f32_e32 v142, v142
	v_mul_f32_e32 v143, 0xbfb8aa3b, v143
	v_mul_f32_e32 v145, 0xbfb8aa3b, v145
	v_mul_f32_e32 v146, 0xbfb8aa3b, v146
	v_mul_f32_e32 v141, 0xbfb8aa3b, v141
	v_exp_f32_e32 v139, v139
	v_exp_f32_e32 v143, v143
	v_exp_f32_e32 v145, v145
	v_exp_f32_e32 v146, v146
	v_exp_f32_e32 v141, v141
	v_add_f32_e32 v138, 1.0, v138
	v_add_f32_e32 v142, 1.0, v142
	v_fma_f32 v128, v0, v140, v156
	v_rcp_f32_e32 v138, v138
	v_add_f32_e32 v139, 1.0, v139
	v_rcp_f32_e32 v142, v142
	v_add_f32_e32 v143, 1.0, v143
	v_add_f32_e32 v145, 1.0, v145
	v_add_f32_e32 v146, 1.0, v146
	v_add_f32_e32 v141, 1.0, v141
	v_mul_f32_e32 v128, 0xbfb8aa3b, v128
	v_fma_f32 v129, v1, v140, v157
	v_rcp_f32_e32 v139, v139
	v_rcp_f32_e32 v143, v143
	v_rcp_f32_e32 v145, v145
	v_rcp_f32_e32 v146, v146
	v_rcp_f32_e32 v141, v141
	v_exp_f32_e32 v128, v128
	v_mul_f32_e32 v129, 0xbfb8aa3b, v129
	v_fma_f32 v130, v2, v140, v158
	v_exp_f32_e32 v129, v129
	v_mul_f32_e32 v130, 0xbfb8aa3b, v130
	v_exp_f32_e32 v130, v130
	v_cvt_pk_bf16_f32 v142, v138, v142
	v_add_co_u32_e32 v138, vcc, s85, v136
	v_cvt_pk_bf16_f32 v143, v143, v146
	v_cvt_pk_bf16_f32 v144, v139, v144
	v_cvt_pk_bf16_f32 v145, v145, v141
	v_addc_co_u32_e32 v139, vcc, 0, v137, vcc
	v_add_f32_e32 v128, 1.0, v128
	global_store_dwordx4 v[138:139], v[142:145], off
	v_fma_f32 v132, v4, v140, v160
	v_rcp_f32_e32 v138, v128
	v_fma_f32 v128, v5, v140, v161
	v_add_f32_e32 v129, 1.0, v129
	v_mul_f32_e32 v132, 0xbfb8aa3b, v132
	v_mul_f32_e32 v128, 0xbfb8aa3b, v128
	v_rcp_f32_e32 v133, v129
	v_fma_f32 v129, v6, v140, v162
	v_add_f32_e32 v130, 1.0, v130
	v_fma_f32 v135, v7, v140, v163
	v_fma_f32 v131, v3, v140, v159
	v_exp_f32_e32 v132, v132
	v_exp_f32_e32 v128, v128
	v_mul_f32_e32 v129, 0xbfb8aa3b, v129
	v_rcp_f32_e32 v134, v130
	v_mul_f32_e32 v130, 0xbfb8aa3b, v135
	v_mul_f32_e32 v131, 0xbfb8aa3b, v131
	v_exp_f32_e32 v129, v129
	v_exp_f32_e32 v130, v130
	v_exp_f32_e32 v131, v131
	v_add_f32_e32 v132, 1.0, v132
	v_add_f32_e32 v128, 1.0, v128
	v_rcp_f32_e32 v132, v132
	v_rcp_f32_e32 v128, v128
	v_add_f32_e32 v129, 1.0, v129
	v_add_f32_e32 v130, 1.0, v130
	v_add_f32_e32 v131, 1.0, v131
	v_rcp_f32_e32 v129, v129
	v_rcp_f32_e32 v130, v130
	v_rcp_f32_e32 v131, v131
	v_cvt_pk_bf16_f32 v128, v132, v128
	v_add_co_u32_e32 v132, vcc, 0x1e000, v136
	v_cvt_pk_bf16_f32 v129, v129, v130
	v_cvt_pk_bf16_f32 v130, v138, v133
	v_cvt_pk_bf16_f32 v131, v134, v131
	v_addc_co_u32_e32 v133, vcc, 0, v137, vcc
	global_store_dwordx4 v[132:133], v[128:131], off
